# XCD-local grid barrier after FFN-in and after Wout, guarded by a runtime check that every cb%8 group shares one XCC (falls back to the full barrier otherwise)
# speedup vs baseline: 1.0248x; 1.0008x over previous
; #define LAS __attribute__((address_space(3)))
; __device__ __forceinline__ unsigned xb_add(unsigned* p, unsigned v) { return __hip_atomic_fetch_add(p, v, __ATOMIC_RELAXED, __HIP_MEMORY_SCOPE_AGENT); }
; __device__ __forceinline__ unsigned xb_xcc_id() { return (unsigned)__builtin_amdgcn_s_getreg((3 << 11) | 20) & 0xFu; }
; __device__ __forceinline__ XcdBarrier xcd_barrier_post(unsigned* bar, volatile LAS unsigned* st) {
;     XcdBarrier b; b.bar = bar; b.x = xb_xcc_id(); b.st = st;
;     if (threadIdx.x == 0) (void)xb_add(&bar[XB_XCNT(b.x)], 1u);
;     return b;
; }
; __global__ void __launch_bounds__(512, 2) mk_fwd(Args a) {
;     extern __shared__ __attribute__((aligned(16))) unsigned char lds_raw[];
;     LAS unsigned char* lds = (LAS unsigned char*)lds_raw;
;     cg::grid_group grid = cg::this_grid();
;     const int G = gridDim.x, cb = blockIdx.x; const int vcu = (G % 8 == 0) ? (cb % 8) * (G / 8) + cb / 8 : cb;
;     unsigned char* ws = a.ws; unsigned char* wt = ws + WS_WT;
;     volatile LAS unsigned* MISC = (volatile LAS unsigned*)(lds + LDS_MISC);
;     if (threadIdx.x < 4) MISC[threadIdx.x] = 0u;
;     __syncthreads();
;     const XcdBarrier bar = xcd_barrier_post((unsigned*)(ws + WS_CTL), MISC);
.LBB0_2:
	s_load_dword s16, s[0:1], 0x98
	s_load_dwordx4 s[4:7], s[0:1], 0x80
	v_and_b32_e32 v193, 0x3ff, v0
	v_cmp_gt_u32_e32 vcc, 4, v193
	s_waitcnt lgkmcnt(0)
	v_writelane_b32 v251, s4, 2
	s_nop 1
	v_writelane_b32 v251, s5, 3
	v_writelane_b32 v251, s6, 4
	v_writelane_b32 v251, s7, 5
	s_and_saveexec_b64 s[4:5], vcc
	v_lshl_add_u32 v1, v193, 2, 0
	v_add_u32_e32 v1, 0x20800, v1
	v_mov_b32_e32 v2, 0
	ds_write_b32 v1, v2
	s_or_b64 exec, exec, s[4:5]
	v_cmp_eq_u32_e64 s[2:3], 0, v193
	s_waitcnt lgkmcnt(0)
	s_barrier
	s_getreg_b32 s4, hwreg(HW_REG_XCC_ID, 0, 4)
	v_writelane_b32 v251, s2, 6
	s_and_b32 s17, s4, 15
	s_nop 0
	v_writelane_b32 v251, s3, 7
	s_and_saveexec_b64 s[4:5], s[2:3]
	s_cbranch_execz .LBB0_7
	s_mov_b64 s[6:7], exec
	v_mbcnt_lo_u32_b32 v1, s6, 0
	v_mbcnt_hi_u32_b32 v1, s7, v1
	v_cmp_eq_u32_e32 vcc, 0, v1
	s_and_b64 s[8:9], exec, vcc
	s_mov_b64 exec, s[8:9]
	s_cbranch_execz .LBB0_7
	s_lshl_b32 s8, s17, 8
	v_mov_b32_e32 v1, s8
	s_load_dwordx4 s[8:11], s[0:1], 0x80
	s_bcnt1_i32_b64 s6, s[6:7]
	v_mov_b32_e32 v2, s6
	s_waitcnt lgkmcnt(0)
	global_atomic_add v1, v2, s[10:11] offset:1024
	v_readlane_b32 s6, v251, 0
	s_add_i32 s7, s17, 1
	s_lshl_b32 s6, s6, 2
	s_add_i32 s6, s6, 0x3840
	v_mov_b32_e32 v1, s6
	v_mov_b32_e32 v2, s7
	global_store_dword v1, v2, s[10:11]

; #define LAS __attribute__((address_space(3)))
; __device__ __forceinline__ unsigned xb_ld(unsigned* p)              { return __hip_atomic_load(p, __ATOMIC_RELAXED, __HIP_MEMORY_SCOPE_AGENT); }
; __device__ __forceinline__ void xcd_barrier_complete(unsigned* bar, unsigned x, unsigned& nloc, unsigned& nx) {
;     ...
;         for (unsigned j = 0; j < 16; ++j) { const unsigned c = xb_ld(&bar[XB_XCNT(j)]); sum += c; cnt += (c > 0u) ? 1u : 0u; mine = (j == x) ? c : mine; }
;         if (sum == G) break;
;         __builtin_amdgcn_s_sleep(1);
;         if ((++sp & 255u) == 0u) { if (xb_ld(&bar[XB_TMO])) break; if (sp > XB_SPIN_CAP) { atomicAdd(&bar[XB_TMO], 1u); break; } }
;     }
;     nloc = mine > 0u ? mine : 1u; nx = cnt > 0u ? cnt : 1u;
; __global__ void __launch_bounds__(512, 2) mk_fwd(Args a) {
;     ...
;     const int G = gridDim.x, cb = blockIdx.x; const int vcu = (G % 8 == 0) ? (cb % 8) * (G / 8) + cb / 8 : cb;
;     unsigned char* ws = a.ws; unsigned char* wt = ws + WS_WT;
;     volatile LAS unsigned* MISC = (volatile LAS unsigned*)(lds + LDS_MISC);
;     if (threadIdx.x < 4) MISC[threadIdx.x] = 0u;
;     __syncthreads();
;     const XcdBarrier bar = xcd_barrier_post((unsigned*)(ws + WS_CTL), MISC);
;     init_phase(a, G);
;     convert_layer(a, 0, lds, G);
;     grid.sync();
;     for (int l = 0; l < DEPTH; ++l) {
;         if (l > 0) { convert_layer(a, l, lds, G); xcd_barrier(bar); }
;         for (int half = 0; half < 2; ++half) {
;             const int S = half ? 8192 : 4096, N1 = half ? 64 : 32, lgN1 = half ? 6 : 5, NB = half ? 4 : 8;
;             const size_t r0 = (size_t)half * MH;
;             bf16_t* XBh = (bf16_t*)(ws + WS_XB) + r0 * DM; float* ssqh = (float*)(ws + WS_SSQ) + r0 * 16; float* outh = a.out + r0 * DM;
;             unsigned char* R = ws + WS_R;
.LBB0_91:
	s_or_b64 exec, exec, s[0:1]
	v_readlane_b32 s36, v251, 2
	v_readlane_b32 s38, v251, 4
	v_readlane_b32 s39, v251, 5
	s_add_u32 s58, s38, 0x500000
	s_addc_u32 s59, s39, 0
	s_add_u32 s0, s38, 0x2f00000
	s_addc_u32 s1, s39, 0
	s_add_u32 s18, s38, 0x2200000
	v_readlane_b32 s37, v251, 3
	v_writelane_b32 v251, s0, 31
	s_addc_u32 s19, s39, 0
	s_mov_b64 s[4:5], s[40:41]
	v_writelane_b32 v251, s1, 32
	s_add_u32 s0, s38, 0x2000400
	s_addc_u32 s1, s39, 0
	s_add_u32 s20, s38, 0x2000000
	s_addc_u32 s21, s39, 0
	s_add_u32 s22, s38, 0x1880000
	v_writelane_b32 v251, s0, 33
	s_addc_u32 s23, s39, 0
	s_mov_b64 s[6:7], s[42:43]
	v_writelane_b32 v251, s1, 34
	s_add_u32 s0, s38, 0x1300000
	s_addc_u32 s1, s39, 0
	v_writelane_b32 v251, s0, 35
	s_mov_b64 s[8:9], s[44:45]
	s_mov_b64 s[10:11], s[46:47]
	v_writelane_b32 v251, s1, 36
	s_mov_b64 s[12:13], s[48:49]
	s_mov_b64 s[14:15], s[50:51]
	v_writelane_b32 v251, s0, 37
	s_cmp_lg_u64 s[46:47], 0
	s_mov_b32 s71, 0
	v_writelane_b32 v251, s1, 38
	v_writelane_b32 v251, s2, 39
	v_writelane_b32 v251, s3, 40
	v_writelane_b32 v251, s4, 41
	v_writelane_b32 v251, s5, 42
	v_writelane_b32 v251, s6, 43
	v_writelane_b32 v251, s7, 44
	v_writelane_b32 v251, s8, 45
	v_writelane_b32 v251, s9, 46
	v_writelane_b32 v251, s10, 47
	v_writelane_b32 v251, s11, 48
	v_writelane_b32 v251, s12, 49
	v_writelane_b32 v251, s13, 50
	v_writelane_b32 v251, s14, 51
	v_writelane_b32 v251, s15, 52
	s_cselect_b64 s[0:1], -1, 0
	v_writelane_b32 v251, s0, 53
	s_mov_b32 s31, s71
	s_mov_b32 s89, 0x41880000
	v_writelane_b32 v251, s1, 54
	s_add_u32 s0, s38, 0x200
	s_addc_u32 s1, s39, 0
	v_writelane_b32 v251, s0, 55
	v_mov_b32_e32 v1, 0
	v_mov_b32_e32 v234, 1
	v_writelane_b32 v251, s1, 56
	s_add_u32 s0, s38, 0x1000
	s_addc_u32 s1, s39, 0
	v_writelane_b32 v251, s0, 57
	v_mbcnt_hi_u32_b32 v235, -1, v35
	v_mov_b32_e32 v192, 0x358637bd
	v_writelane_b32 v251, s1, 58
	s_add_u32 s0, s38, 0x1100
	s_addc_u32 s1, s39, 0
	v_writelane_b32 v251, s0, 59
	v_mov_b64_e32 v[194:195], 0xb00
	v_mov_b64_e32 v[196:197], 0xaff
	v_writelane_b32 v251, s1, 60
	s_add_u32 s0, s38, 0x1200
	s_addc_u32 s1, s39, 0
	v_writelane_b32 v251, s0, 61
	v_mov_b64_e32 v[198:199], 0x200
	v_mov_b64_e32 v[200:201], 0x1ff
	v_writelane_b32 v251, s1, 62
	s_add_u32 s0, s38, 0x1300
	s_addc_u32 s1, s39, 0
	v_writelane_b32 v251, s0, 63
	s_cmp_eq_u32 s17, 15
	v_readlane_b32 s15, v251, 0
	v_writelane_b32 v252, s1, 0
	s_cselect_b64 s[0:1], -1, 0
	v_writelane_b32 v252, s0, 1
	s_cmp_eq_u32 s17, 14
	v_readlane_b32 s10, v251, 29
	v_writelane_b32 v252, s1, 2
	s_cselect_b64 s[0:1], -1, 0
	v_writelane_b32 v252, s0, 3
	s_cmp_eq_u32 s17, 13
	v_readlane_b32 s11, v251, 30
	v_writelane_b32 v252, s1, 4
	s_cselect_b64 s[0:1], -1, 0
	v_writelane_b32 v252, s0, 5
	s_cmp_eq_u32 s17, 12
	v_mov_b32_e32 v236, 0x42800000
	v_writelane_b32 v252, s1, 6
	s_cselect_b64 s[0:1], -1, 0
	v_writelane_b32 v252, s0, 7
	s_cmp_eq_u32 s17, 11
	v_mov_b32_e32 v237, 0xf149f2ca
	v_writelane_b32 v252, s1, 8
	s_cselect_b64 s[0:1], -1, 0
	v_writelane_b32 v252, s0, 9
	s_cmp_eq_u32 s17, 10
	v_mov_b32_e32 v202, 0x40c00000
	v_writelane_b32 v252, s1, 10
	s_cselect_b64 s[0:1], -1, 0
	v_writelane_b32 v252, s0, 11
	s_cmp_eq_u32 s17, 9
	v_mov_b32_e32 v204, 0x40e00000
	v_writelane_b32 v252, s1, 12
	s_cselect_b64 s[0:1], -1, 0
	v_writelane_b32 v252, s0, 13
	s_cmp_eq_u32 s17, 8
	s_movk_i32 s57, 0x5800
	v_writelane_b32 v252, s1, 14
	s_cselect_b64 s[0:1], -1, 0
	v_writelane_b32 v252, s0, 15
	s_cmp_eq_u32 s17, 7
	s_movk_i32 s61, 0x90
	v_writelane_b32 v252, s1, 16
	s_cselect_b64 s[0:1], -1, 0
	v_writelane_b32 v252, s0, 17
	s_cmp_eq_u32 s17, 6
	s_mov_b32 s33, 0x2aaaaaab
	v_writelane_b32 v252, s1, 18
	s_cselect_b64 s[0:1], -1, 0
	v_writelane_b32 v252, s0, 19
	s_cmp_eq_u32 s17, 5
	s_mov_b32 s64, 0
	v_writelane_b32 v252, s1, 20
	s_cselect_b64 s[0:1], -1, 0
	v_writelane_b32 v252, s0, 21
	s_cmp_eq_u32 s17, 4
	s_mov_b32 s60, 0x3fb8aa3b
	v_writelane_b32 v252, s1, 22
	s_cselect_b64 s[0:1], -1, 0
	v_writelane_b32 v252, s0, 23
	s_cmp_eq_u32 s17, 3
	s_mov_b32 s53, 0x42040000
	v_writelane_b32 v252, s1, 24
	s_cselect_b64 s[0:1], -1, 0
	v_writelane_b32 v252, s0, 25
	s_cmp_eq_u32 s17, 2
	s_mov_b32 s91, 0x42440000
	v_writelane_b32 v252, s1, 26
	s_cselect_b64 s[0:1], -1, 0
	v_writelane_b32 v252, s0, 27
	s_cmp_eq_u32 s17, 1
	s_mov_b32 s65, 0x42e20000
	v_writelane_b32 v252, s1, 28
	s_cselect_b64 s[0:1], -1, 0
	v_writelane_b32 v252, s0, 29
	s_cmp_eq_u32 s17, 0
	s_barrier
;     __device__ bool next(int i, Unit& u) const { const int L = i * G + c; if (L >= 512) return false; u.pm = 0; u.pn = L; u.offA = 0; u.offB = (size_t)L * 256 * 256 * 2; return true; }
; __device__ __forceinline__ unsigned xb_ld(unsigned* p)              { return __hip_atomic_load(p, __ATOMIC_RELAXED, __HIP_MEMORY_SCOPE_AGENT); }
; __device__ __forceinline__ unsigned xb_add(unsigned* p, unsigned v) { return __hip_atomic_fetch_add(p, v, __ATOMIC_RELAXED, __HIP_MEMORY_SCOPE_AGENT); }
;     __device__ bool next(int i, Unit& u) const { const int v = lo + vcu + G * i; if (v >= hi) return false;
;         if (v < 384) { u.pm = (v * 21846) >> 16; u.pn = v - 3 * u.pm; } else { const int w = v - 384; u.pm = w >> 3; u.pn = 3 + (w & 7); }
;         u.offA = (size_t)u.pm * 256 * 1024 * 2; u.offB = (size_t)u.pn * 256 * 1024 * 2; return true; }
;     __device__ bool next(int i, Unit& u) const { int L;
;         if (G == 256) { if (vcu < 128) { if (i >= 1) return false; L = vcu; } else { if (i >= 3) return false; L = 128 + (vcu - 128) * 3 + i; } }
;         else { L = i * G + c; if (L >= 512) return false; }
;         u.pm = 0; u.pn = L; u.offA = 0; u.offB = (size_t)L * 256 * 256 * 2; return true; }
; __device__ __forceinline__ void xcd_barrier(const XcdBarrier& b) {
;     ...
;         unsigned* bar = b.bar;
;         __builtin_amdgcn_s_waitcnt(0);
;         unsigned nloc = b.st[0], nx = b.st[1];
;         if (nloc == 0u) { xcd_barrier_complete(bar, b.x, nloc, nx); b.st[0] = nloc; b.st[1] = nx; }
;         const unsigned old = xb_add(&bar[XB_XSUB(b.x)], 1u);
;         const unsigned gen = old / nloc;
;         if (old + 1u == (gen + 1u) * nloc) {
;             __builtin_amdgcn_fence(__ATOMIC_RELEASE, "agent");
;             asm volatile("s_waitcnt vmcnt(0)" ::: "memory");
;             const unsigned og = xb_add(&bar[XB_TOP], 1u);
;             const unsigned tg = og / nx;
;             if (og + 1u == (tg + 1u) * nx) xb_add(&bar[XB_TOPGEN], 1u);
;             else XB_SPIN(xb_ld(&bar[XB_TOPGEN]) == tg, bar);
;             __builtin_amdgcn_fence(__ATOMIC_ACQUIRE, "agent");
;             xb_add(&bar[XB_XGEN(b.x)], 1u);
;             asm volatile("s_waitcnt vmcnt(0)" ::: "memory");
;         } else {
;             XB_SPIN(xb_ld(&bar[XB_XGEN(b.x)]) == gen, bar);
	v_writelane_b32 v252, s1, 30
	s_cselect_b64 s[0:1], -1, 0
	v_writelane_b32 v252, s0, 31
	s_nop 1
	v_writelane_b32 v252, s1, 32
	s_lshl_b32 s0, s17, 8
	s_add_u32 s0, s38, s0
	s_addc_u32 s1, s39, 0
	s_add_u32 s2, s0, 0x1400
	s_addc_u32 s3, s1, 0
	v_writelane_b32 v252, s2, 33
	s_add_u32 s0, s0, 0x2400
	s_addc_u32 s1, s1, 0
	v_writelane_b32 v252, s3, 34
	v_writelane_b32 v252, s0, 35
	v_readlane_b32 s17, v251, 1
	s_mul_i32 s6, s17, 0x5556
	v_writelane_b32 v252, s1, 36
	s_add_u32 s0, s38, 0x3400
	s_addc_u32 s1, s39, 0
	v_writelane_b32 v252, s0, 37
	s_nop 1
	v_writelane_b32 v252, s1, 38
	s_add_u32 s0, s38, 0x3500
	s_addc_u32 s1, s39, 0
	v_writelane_b32 v252, s0, 39
	s_nop 1
	v_writelane_b32 v252, s1, 40
	s_add_u32 s0, s38, 0x100000
	v_writelane_b32 v252, s0, 41
	s_addc_u32 s0, s39, 0
	s_add_u32 s66, s38, 0xb800000
	s_addc_u32 s67, s39, 0
	s_cmpk_lt_i32 s15, 0xb00
	v_writelane_b32 v252, s0, 42
	s_cselect_b64 s[0:1], -1, 0
	v_writelane_b32 v252, s0, 43
	s_nop 1
	v_writelane_b32 v252, s1, 44
	s_ashr_i32 s0, s15, 31
	v_writelane_b32 v252, s0, 45
	s_lshr_b32 s0, s0, 29
	s_add_i32 s0, s15, s0
	s_ashr_i32 s2, s0, 3
	s_and_b32 s0, s0, -8
	s_sub_i32 s3, s15, s0
	s_ashr_i32 s0, s92, 31
	s_cmpk_lt_i32 s15, 0x200
	s_cselect_b64 s[24:25], -1, 0
	s_lshl_b32 s4, s3, 6
	s_add_u32 s94, s38, 0xe800000
	s_addc_u32 s95, s39, 0
	s_add_u32 s62, s38, 0x12800000
	s_addc_u32 s63, s39, 0
	s_add_u32 s68, s38, 0x16800000
	s_addc_u32 s69, s39, 0
	s_add_u32 s54, s38, 0x1a800000
	s_addc_u32 s55, s39, 0
	s_add_u32 s26, s38, 0x1e800000
	s_addc_u32 s27, s39, 0
	s_cmpk_lt_i32 s17, 0x200
	v_writelane_b32 v252, s0, 46
	s_cselect_b64 s[0:1], -1, 0
	v_writelane_b32 v252, s0, 47
	s_ashr_i32 s7, s6, 16
	s_ashr_i32 s28, s17, 2
	v_writelane_b32 v252, s1, 48
	s_add_i32 s0, s17, 0xfffffe80
	s_lshr_b32 s5, s0, 3
	s_and_b32 s0, s17, 7
	s_add_i32 s8, s0, 3
	s_mul_i32 s0, s7, -3
	s_add_i32 s9, s0, s17
	s_and_b32 s0, s17, 3
	v_writelane_b32 v252, s0, 49
	s_lshl_b32 s0, s0, 19
	s_add_u32 s0, s10, s0
	s_addc_u32 s1, s11, 0
	s_add_u32 s10, s0, 0x40000
	v_writelane_b32 v252, s0, 50
	s_addc_u32 s11, s1, 0
	s_nop 0
	v_writelane_b32 v252, s1, 51
	v_writelane_b32 v252, s10, 52
	s_bfe_u32 s0, s15, 0x10002
	s_cmpk_lg_i32 s92, 0x100
	v_writelane_b32 v252, s11, 53
	s_mul_i32 s10, s17, 3
	s_cselect_b64 s[82:83], -1, 0
	s_add_i32 s11, s10, 0xffffff00
	s_cmpk_lt_i32 s17, 0x80
	v_writelane_b32 v252, s0, 54
	s_cselect_b64 s[0:1], -1, 0
	v_writelane_b32 v252, s0, 55
	s_nop 1
	v_writelane_b32 v252, s1, 56
	s_and_b64 s[0:1], s[0:1], exec
	s_cselect_b32 s11, s17, s11
	s_add_u32 s0, s38, 0x510000
	s_addc_u32 s1, s39, 0
	v_writelane_b32 v252, s0, 57
	s_nop 1
	v_writelane_b32 v252, s1, 58
	s_add_u32 s0, s38, 0x500080
	s_addc_u32 s1, s39, 0
	v_writelane_b32 v252, s0, 59
	s_nop 1
	v_writelane_b32 v252, s1, 60
	s_add_i32 s0, s10, 0xffffff01
	s_add_i32 s1, s17, 0x200
	s_cmpk_lt_i32 s17, 0x380
	v_writelane_b32 v252, s0, 61
	s_cselect_b64 s[12:13], -1, 0
	v_writelane_b32 v252, s12, 62
	s_add_i32 s6, s6, 0xaaac00
	s_add_i32 s0, s17, 0x80
	v_writelane_b32 v252, s13, 63
	s_ashr_i32 s12, s6, 16
	s_lshr_b32 s10, s0, 3
	s_mul_i32 s0, s12, -3
	s_add_i32 s13, s0, s1
	s_cmpk_lt_i32 s15, 0x100
	v_writelane_b32 v253, s1, 0
	s_cselect_b64 s[0:1], -1, 0
	v_writelane_b32 v253, s0, 1
	s_ashr_i32 s29, s15, 1
	s_nop 0
	v_writelane_b32 v253, s1, 2
	s_lshl_b32 s0, s15, 8
	s_and_b32 s30, s0, 0x100
	v_writelane_b32 v253, s0, 3
	s_cmp_lt_i32 s3, 0
	s_movk_i32 s0, 0x161
	s_cselect_b32 s0, s0, 0x160
	s_mul_i32 s0, s3, s0
	s_mulk_i32 s3, 0x41
	s_cselect_b32 s1, s3, s4
	s_add_i32 s0, s0, s2
	s_mul_hi_i32 s3, s0, 0x2e8ba2e9
	s_lshr_b32 s4, s3, 31
	s_ashr_i32 s3, s3, 4
	s_add_i32 s3, s3, s4
	s_mul_i32 s4, s3, 0x58
	s_sub_i32 s0, s0, s4
	s_bfe_i32 s4, s0, 0x80000
	s_add_i32 s1, s1, s2
	s_bfe_u32 s4, s4, 0x2000d
	s_ashr_i32 s2, s1, 31
	s_add_i32 s4, s0, s4
	s_lshr_b32 s2, s2, 28
	s_and_b32 s6, s4, 0xfc
	s_add_i32 s2, s1, s2
	s_sub_i32 s0, s0, s6
	s_and_b32 s6, s2, 0xfff0
	s_sub_i32 s1, s1, s6
	s_bfe_i32 s6, s1, 0x80000
	s_bfe_u32 s6, s6, 0x2000d
	s_add_i32 s6, s1, s6
	s_and_b32 s14, s6, 0xfc
	s_sub_i32 s14, s1, s14
	s_lshl_b32 s1, s3, 2
	s_bfe_i32 s3, s4, 0x80000
	s_sext_i32_i16 s3, s3
	s_sext_i32_i8 s0, s0
	s_add_i32 s34, s1, s0
	s_ashr_i32 s0, s3, 2
	v_writelane_b32 v253, s0, 4
	s_lshr_b32 s0, s3, 2
	s_bfe_i64 s[0:1], s[0:1], 0x100000
	s_lshl_b64 s[0:1], s[0:1], 19
	v_writelane_b32 v253, s0, 5
	s_ashr_i32 s35, s34, 31
	s_nop 0
	v_writelane_b32 v253, s1, 6
	s_ashr_i32 s0, s2, 4
	s_bfe_i32 s1, s6, 0x80000
	s_lshl_b32 s0, s0, 2
	s_sext_i32_i16 s1, s1
	s_sext_i32_i8 s2, s14
	s_add_i32 s36, s0, s2
	s_ashr_i32 s0, s1, 2
	v_writelane_b32 v253, s0, 7
	s_lshl_b64 s[2:3], s[34:35], 19
	v_writelane_b32 v253, s2, 8
	s_lshr_b32 s0, s1, 2
	s_ashr_i32 s37, s36, 31
	v_writelane_b32 v253, s3, 9
	s_mov_b32 s2, s34
	v_writelane_b32 v253, s2, 10
	s_bfe_i64 s[0:1], s[0:1], 0x100000
	s_nop 0
	v_writelane_b32 v253, s3, 11
	s_lshl_b64 s[2:3], s[34:35], 14
	s_cmpk_lt_i32 s17, 0x180
	s_cselect_b32 s34, s7, s5
	v_writelane_b32 v253, s2, 12
	s_cselect_b32 s4, s9, s8
	s_ashr_i32 s35, s34, 31
	v_writelane_b32 v253, s3, 13
	s_lshl_b64 s[2:3], s[34:35], 19
	v_writelane_b32 v253, s2, 14
	s_ashr_i32 s5, s4, 31
	s_nop 0
	v_writelane_b32 v253, s3, 15
	s_mov_b32 s2, s4
	v_writelane_b32 v253, s2, 16
	s_nop 1
	v_writelane_b32 v253, s3, 17
	s_lshl_b64 s[2:3], s[4:5], 19
	s_cmpk_eq_i32 s92, 0x100
	s_cselect_b64 s[4:5], -1, 0
	s_and_b64 s[6:7], s[4:5], exec
	v_writelane_b32 v253, s24, 18
	s_cselect_b32 s6, s11, s15
	s_or_b64 s[4:5], s[4:5], s[24:25]
	v_writelane_b32 v253, s25, 19
	v_writelane_b32 v253, s4, 20
	s_ashr_i32 s7, s6, 31
	s_mov_b32 s25, 0x42a20000
	v_writelane_b32 v253, s5, 21
;     __device__ bool next(int i, Unit& u) const { const int L = i * G + c; if (L >= 512) return false; u.pm = 0; u.pn = L; u.offA = 0; u.offB = (size_t)L * 256 * 256 * 2; return true; }
; __device__ __forceinline__ unsigned xb_ld(unsigned* p)              { return __hip_atomic_load(p, __ATOMIC_RELAXED, __HIP_MEMORY_SCOPE_AGENT); }
;     __device__ bool next(int i, Unit& u) const { const int v = lo + vcu + G * i; if (v >= hi) return false;
;         if (v < 384) { u.pm = (v * 21846) >> 16; u.pn = v - 3 * u.pm; } else { const int w = v - 384; u.pm = w >> 3; u.pn = 3 + (w & 7); }
;         u.offA = (size_t)u.pm * 256 * 1024 * 2; u.offB = (size_t)u.pn * 256 * 1024 * 2; return true; }
;     __device__ bool next(int i, Unit& u) const { int L;
;         if (G == 256) { if (vcu < 128) { if (i >= 1) return false; L = vcu; } else { if (i >= 3) return false; L = 128 + (vcu - 128) * 3 + i; } }
;         else { L = i * G + c; if (L >= 512) return false; }
;         u.pm = 0; u.pn = L; u.offA = 0; u.offB = (size_t)L * 256 * 256 * 2; return true; }
;         const int chalf = L & 1, k2g = (L >> 1) % ng, b = (L >> 1) / ng; u.offA = 0; u.offB = (((size_t)b * 512 + chalf * 256) * (256 * (size_t)N1) + (size_t)k2g * 512) * 2; return true; }
; __device__ __forceinline__ void xcd_barrier_complete(unsigned* bar, unsigned x, unsigned& nloc, unsigned& nx) {
;     const unsigned G = gridDim.x * gridDim.y * gridDim.z;
;     unsigned sum, cnt, mine, sp = 0u;
;     for (;;) {
;         sum = 0u; cnt = 0u; mine = 0u;
; #pragma unroll
;         for (unsigned j = 0; j < 16; ++j) { const unsigned c = xb_ld(&bar[XB_XCNT(j)]); sum += c; cnt += (c > 0u) ? 1u : 0u; mine = (j == x) ? c : mine; }
;         if (sum == G) break;
;         __builtin_amdgcn_s_sleep(1);
;         if ((++sp & 255u) == 0u) { if (xb_ld(&bar[XB_TMO])) break; if (sp > XB_SPIN_CAP) { atomicAdd(&bar[XB_TMO], 1u); break; } }
;     }
;     nloc = mine > 0u ? mine : 1u; nx = cnt > 0u ? cnt : 1u;
; }
	s_mov_b32 s4, s6
	v_writelane_b32 v253, s4, 22
	s_nop 1
	v_writelane_b32 v253, s5, 23
	s_lshl_b64 s[4:5], s[6:7], 17
	s_add_u32 s4, s68, s4
	s_addc_u32 s5, s69, s5
	s_add_u32 s6, s4, 0x10000
	s_addc_u32 s7, s5, 0
	v_writelane_b32 v253, s6, 24
	s_nop 1
	v_writelane_b32 v253, s7, 25
	s_add_u32 s6, s4, 0x10080
	v_writelane_b32 v253, s4, 26
	s_addc_u32 s7, s5, 0
	s_cmpk_lt_i32 s17, 0xff80
	v_writelane_b32 v253, s5, 27
	v_writelane_b32 v253, s6, 28
	s_cselect_b32 s12, s12, s10
	s_nop 0
	v_writelane_b32 v253, s7, 29
	s_cselect_b32 s6, s13, s8
	s_ashr_i32 s13, s12, 31
	s_lshl_b64 s[4:5], s[12:13], 19
	v_writelane_b32 v253, s4, 30
	s_ashr_i32 s7, s6, 31
	s_lshl_b64 s[0:1], s[0:1], 19
	v_writelane_b32 v253, s5, 31
	s_mov_b32 s4, s6
	v_writelane_b32 v253, s4, 32
	s_nop 1
	v_writelane_b32 v253, s5, 33
	s_lshl_b64 s[4:5], s[6:7], 19
	s_lshl_b64 s[6:7], s[36:37], 19
	s_add_u32 s8, s20, s0
	v_writelane_b32 v253, s20, 34
	s_addc_u32 s9, s21, s1
	s_add_u32 s10, s8, 0x40000
	v_writelane_b32 v253, s21, 35
	s_addc_u32 s11, s9, 0
	v_writelane_b32 v253, s10, 36
	s_nop 1
	v_writelane_b32 v253, s11, 37
	s_add_u32 s10, s26, s6
	v_writelane_b32 v253, s26, 38
	s_addc_u32 s11, s27, s7
	s_add_u32 s20, s10, 0x40000
	v_writelane_b32 v253, s27, 39
	v_writelane_b32 v253, s10, 40
	s_addc_u32 s21, s11, 0
	s_nop 0
	v_writelane_b32 v253, s11, 41
	v_writelane_b32 v253, s20, 42
	s_add_u32 s10, s8, 0x40080
	s_nop 0
	v_writelane_b32 v253, s21, 43
	v_writelane_b32 v253, s8, 44
	s_addc_u32 s11, s9, 0
	s_nop 0
	v_writelane_b32 v253, s9, 45
	v_writelane_b32 v253, s10, 46
	s_mul_i32 s9, s36, 0x160000
	s_mul_hi_i32 s8, s36, 0x160000
	v_writelane_b32 v253, s11, 47
	s_mov_b32 s10, s36
	v_writelane_b32 v253, s10, 48
	s_nop 1
	v_writelane_b32 v253, s11, 49
	s_add_u32 s10, s66, s9
	s_addc_u32 s11, s67, s8
	s_add_u32 s8, s10, 0xb0000
	v_writelane_b32 v253, s10, 50
	s_addc_u32 s9, s11, 0
	s_nop 0
	v_writelane_b32 v253, s11, 51
	v_writelane_b32 v253, s8, 52
	s_nop 1
	v_writelane_b32 v253, s9, 53
	s_mov_b32 s8, s34
	v_writelane_b32 v253, s8, 54
	s_nop 1
	v_writelane_b32 v253, s9, 55
	s_lshl_b64 s[8:9], s[34:35], 14
	s_add_u32 s2, s22, s2
	v_writelane_b32 v253, s8, 56
	s_addc_u32 s3, s23, s3
	s_nop 0
	v_writelane_b32 v253, s9, 57
	s_add_u32 s8, s2, 0x40000
	s_addc_u32 s9, s3, 0
	v_writelane_b32 v253, s8, 58
	s_nop 1
	v_writelane_b32 v253, s9, 59
	s_add_u32 s8, s2, 0x40080
	v_writelane_b32 v253, s2, 60
	s_addc_u32 s9, s3, 0
	s_nop 0
	v_writelane_b32 v253, s3, 61
	s_mov_b32 s2, s12
	v_writelane_b32 v254, s2, 0
	v_writelane_b32 v253, s8, 62
	s_nop 0
	v_writelane_b32 v254, s3, 1
	s_lshl_b64 s[2:3], s[12:13], 14
	v_writelane_b32 v254, s2, 2
	v_writelane_b32 v253, s9, 63
	s_mov_b32 s13, 0x43010000
	v_writelane_b32 v254, s3, 3
	s_add_u32 s2, s22, s4
	v_writelane_b32 v254, s22, 4
	s_addc_u32 s3, s23, s5
	s_add_u32 s4, s2, 0x40000
	v_writelane_b32 v254, s23, 5
	s_addc_u32 s5, s3, 0
	v_writelane_b32 v254, s4, 6
	s_nop 1
	v_writelane_b32 v254, s5, 7
	s_add_u32 s4, s2, 0x40080
	v_writelane_b32 v254, s2, 8
	s_addc_u32 s5, s3, 0
	s_nop 0
	v_writelane_b32 v254, s3, 9
	v_writelane_b32 v254, s4, 10
	s_add_u32 s2, s18, s0
	s_nop 0
	v_writelane_b32 v254, s5, 11
	v_writelane_b32 v254, s18, 12
	s_addc_u32 s3, s19, s1
	s_add_u32 s0, s2, 0x40000
	v_writelane_b32 v254, s19, 13
	s_addc_u32 s1, s3, 0
	v_writelane_b32 v254, s0, 14
	s_add_u32 s4, s54, s6
	s_addc_u32 s5, s55, s7
	v_writelane_b32 v254, s1, 15
	s_mul_i32 s0, s93, s92
	s_mul_i32 s0, s0, s16
	v_writelane_b32 v254, s0, 16
	v_writelane_b32 v254, s30, 17
	s_add_u32 s0, s4, 0x40000
	s_mov_b32 s93, 0x800000
	v_writelane_b32 v254, s31, 18
	v_writelane_b32 v254, s4, 19
	s_addc_u32 s1, s5, 0
	s_movk_i32 s6, 0x330
	v_writelane_b32 v254, s5, 20
	v_writelane_b32 v254, s0, 21
	s_mov_b64 s[18:19], 0x80
	s_mov_b32 s31, 0x42820000
	v_writelane_b32 v254, s1, 22
	s_add_u32 s0, s2, 0x40080
	v_writelane_b32 v254, s2, 23
	s_addc_u32 s1, s3, 0
	s_lshl_b32 s52, s92, 4
	v_writelane_b32 v254, s3, 24
	v_writelane_b32 v254, s0, 25
	s_lshl_b32 s56, s92, 8
	s_nop 0
	v_writelane_b32 v254, s1, 26
	s_ashr_i32 s0, s17, 31
	v_writelane_b32 v254, s0, 27
	v_writelane_b32 v254, s28, 28
	s_abs_i32 s0, s28
	v_writelane_b32 v254, s0, 29
	v_writelane_b32 v254, s29, 30
	s_abs_i32 s0, s29
	v_writelane_b32 v254, s0, 31
	s_lshl_b32 s0, s15, 4
	s_bitcmp1_b32 s17, 0
	v_writelane_b32 v254, s0, 32
	s_cselect_b64 s[0:1], -1, 0
	v_writelane_b32 v254, s0, 33
	s_bitcmp1_b32 s92, 0
	s_movk_i32 s29, 0x600
	v_writelane_b32 v254, s1, 34
	s_cselect_b64 s[0:1], -1, 0
	v_writelane_b32 v254, s0, 35
	s_mov_b32 s28, 0x3a800000
	s_mov_b32 s17, 0x42c20000
	v_writelane_b32 v254, s1, 36
	s_add_u32 s0, s38, 0x1e800040
	s_addc_u32 s1, s39, 0
	v_writelane_b32 v254, s0, 37
	s_mov_b64 s[14:15], 0x8000
	s_nop 0
	v_writelane_b32 v254, s1, 38
	s_add_u32 s0, s38, 0x510080
	s_addc_u32 s1, s39, 0
	v_writelane_b32 v254, s0, 39
	s_nop 1
	v_writelane_b32 v254, s1, 40
	s_add_u32 s0, s38, 0x20080
	v_writelane_b32 v254, s0, 41
	s_addc_u32 s0, s39, 0
	v_writelane_b32 v254, s0, 42
	s_add_i32 s0, 0, 0x20800
	v_writelane_b32 v254, s0, 43
	s_add_i32 s0, 0, 0x20804
	v_writelane_b32 v254, s0, 44
	v_writelane_b32 v254, s82, 45
	s_nop 1
	v_writelane_b32 v254, s83, 46
	v_writelane_b32 v254, s88, 47
	s_nop 1
	v_writelane_b32 v254, s89, 48
	v_writelane_b32 v254, s52, 49
	v_writelane_b32 v254, s56, 50
	v_mbcnt_lo_u32_b32 v170, -1, 0
	v_mbcnt_hi_u32_b32 v170, -1, v170
	v_and_b32_e32 v171, 7, v170
	v_lshlrev_b32_e32 v170, 2, v170
	v_lshlrev_b32_e32 v171, 2, v171
	s_add_u32 s0, s38, 0x3840
	s_addc_u32 s1, s39, 0
	global_load_dword v172, v170, s[0:1] sc1
	global_load_dword v173, v170, s[0:1] offset:256 sc1
	global_load_dword v174, v170, s[0:1] offset:512 sc1
	global_load_dword v175, v170, s[0:1] offset:768 sc1
	global_load_dword v176, v171, s[0:1] sc1
	s_waitcnt vmcnt(0)
	v_xor_b32_e32 v172, v172, v176
	v_xor_b32_e32 v173, v173, v176
	v_xor_b32_e32 v174, v174, v176
	v_xor_b32_e32 v175, v175, v176
	v_or3_b32 v172, v172, v173, v174
	v_or_b32_e32 v172, v172, v175
	v_cmp_eq_u32_e32 vcc, 0, v176
	v_cmp_ne_u32_e64 s[0:1], 0, v172
	s_nop 3
	s_or_b64 s[0:1], s[0:1], vcc
	s_cmp_eq_u64 s[0:1], 0
	s_cselect_b32 s0, 1, 0
	v_mov_b32_e32 v172, s0
	v_mov_b32_e32 v173, 0x20808
	ds_write_b32 v173, v172
	s_waitcnt lgkmcnt(0)
	s_branch .LBB0_93

; __device__ __forceinline__ unsigned xb_ld(unsigned* p)              { return __hip_atomic_load(p, __ATOMIC_RELAXED, __HIP_MEMORY_SCOPE_AGENT); }
; __device__ __forceinline__ unsigned xb_add(unsigned* p, unsigned v) { return __hip_atomic_fetch_add(p, v, __ATOMIC_RELAXED, __HIP_MEMORY_SCOPE_AGENT); }
; #define XB_SPIN(cond, bar) do { unsigned _sp = 0; while (cond) { __builtin_amdgcn_s_sleep(1); \
;     if ((++_sp & 255u) == 0u) { if (xb_ld(&(bar)[XB_TMO])) break; if (_sp > XB_SPIN_CAP) { atomicAdd(&(bar)[XB_TMO], 1u); break; } } } } while (0)
; __device__ __forceinline__ void xcd_barrier(const XcdBarrier& b) {
;     ...
;         if (nloc == 0u) { xcd_barrier_complete(bar, b.x, nloc, nx); b.st[0] = nloc; b.st[1] = nx; }
;         const unsigned old = xb_add(&bar[XB_XSUB(b.x)], 1u);
;         const unsigned gen = old / nloc;
;         if (old + 1u == (gen + 1u) * nloc) {
;             __builtin_amdgcn_fence(__ATOMIC_RELEASE, "agent");
;             asm volatile("s_waitcnt vmcnt(0)" ::: "memory");
;             const unsigned og = xb_add(&bar[XB_TOP], 1u);
;             const unsigned tg = og / nx;
;             if (og + 1u == (tg + 1u) * nx) xb_add(&bar[XB_TOPGEN], 1u);
;             else XB_SPIN(xb_ld(&bar[XB_TOPGEN]) == tg, bar);
.LBB0_264:
	s_andn2_saveexec_b64 s[8:9], s[8:9]
	s_cbranch_execz .LBB0_284
	s_mov_b64 s[8:9], exec
	v_mov_b32_e32 v3, 0x20808
	ds_read_b32 v3, v3
	s_waitcnt lgkmcnt(0)
	v_readfirstlane_b32 s7, v3
	s_cmp_eq_u32 s7, 1
	s_cbranch_scc1 .Lxl_ffnin
	buffer_wbl2 sc1
	s_waitcnt lgkmcnt(0)
	s_waitcnt vmcnt(0)
	v_mbcnt_lo_u32_b32 v0, s8, 0
	v_mbcnt_hi_u32_b32 v0, s9, v0
	v_cmp_eq_u32_e32 vcc, 0, v0
	s_and_saveexec_b64 s[20:21], vcc
	s_cbranch_execz .LBB0_267
	s_bcnt1_i32_b64 s7, s[8:9]
	v_readlane_b32 s8, v252, 37
	v_mov_b32_e32 v3, s7
	v_readlane_b32 s9, v252, 38
	s_nop 4
	global_atomic_add v3, v1, v3, s[8:9] sc0

; __device__ __forceinline__ unsigned xb_add(unsigned* p, unsigned v) { return __hip_atomic_fetch_add(p, v, __ATOMIC_RELAXED, __HIP_MEMORY_SCOPE_AGENT); }
; __device__ __forceinline__ void xcd_barrier(const XcdBarrier& b) {
;     ...
;             __builtin_amdgcn_fence(__ATOMIC_ACQUIRE, "agent");
;             xb_add(&bar[XB_XGEN(b.x)], 1u);
;             asm volatile("s_waitcnt vmcnt(0)" ::: "memory");
.Lxl_ffnin:
	s_mov_b64 s[8:9], exec
	v_mbcnt_lo_u32_b32 v0, s8, 0
	v_mbcnt_hi_u32_b32 v0, s9, v0
	v_cmp_eq_u32_e32 vcc, 0, v0
	s_waitcnt vmcnt(0)
	buffer_inv sc1
	s_and_saveexec_b64 s[20:21], vcc
	s_cbranch_execz .LBB0_283
	s_bcnt1_i32_b64 s7, s[8:9]
	v_readlane_b32 s8, v252, 35
	v_mov_b32_e32 v0, s7
	v_readlane_b32 s9, v252, 36
	s_nop 4
	global_atomic_add v1, v0, s[8:9]

; __device__ __forceinline__ unsigned xb_add(unsigned* p, unsigned v) { return __hip_atomic_fetch_add(p, v, __ATOMIC_RELAXED, __HIP_MEMORY_SCOPE_AGENT); }
; __device__ __forceinline__ void xcd_barrier(const XcdBarrier& b) {
;     ...
;             __builtin_amdgcn_fence(__ATOMIC_ACQUIRE, "agent");
;             xb_add(&bar[XB_XGEN(b.x)], 1u);
;             asm volatile("s_waitcnt vmcnt(0)" ::: "memory");
.Lxl_wout:
	s_mov_b64 s[8:9], exec
	v_mbcnt_lo_u32_b32 v0, s8, 0
	v_mbcnt_hi_u32_b32 v0, s9, v0
	v_cmp_eq_u32_e32 vcc, 0, v0
	s_waitcnt vmcnt(0)
	buffer_inv sc1
	s_and_saveexec_b64 s[20:21], vcc
	s_cbranch_execz .LBB0_207
	s_bcnt1_i32_b64 s7, s[8:9]
	v_readlane_b32 s8, v252, 35
	v_mov_b32_e32 v0, s7
	v_readlane_b32 s9, v252, 36
	s_nop 4
	global_atomic_add v1, v0, s[8:9]
	s_branch .LBB0_207
